# m10 + 64-bit zeroing of the two 128-register key arrays at the start of each index unit
# speedup vs baseline: 1.0002x; 1.0002x over previous
.LBB0_1292:
	s_waitcnt vmcnt(0)
	v_cndmask_b32_e64 v19, 0, 1, s[78:79]
	v_cmp_ne_u32_e64 s[28:29], 1, v19
	s_andn2_b64 vcc, exec, s[78:79]
	v_lshlrev_b32_e32 v39, 4, v36
	v_lshlrev_b32_e32 v172, 2, v167
	v_lshl_add_u32 v40, v167, 13, 0
	v_lshl_add_u32 v41, v18, 2, s14
	s_waitcnt vmcnt(0) lgkmcnt(0)
	s_barrier
	s_cbranch_vccnz .LBB0_1383
	s_add_i32 s0, s77, 8
	s_lshr_b32 s1, s0, 29
	s_add_i32 s0, s0, s1
	s_ashr_i32 s13, s0, 3
	s_add_i32 s0, 0, 0x22200
	v_add_u32_e32 v173, s0, v39
	v_readlane_b32 s0, v251, 29
	s_add_i32 s14, s13, -2
	s_add_i32 s15, s13, -3
	v_add_u32_e32 v174, s0, v39
	s_max_i32 s0, s13, 2
	s_lshl_b32 s0, s0, 3
	s_add_i32 s0, s0, -8
	s_and_b32 s16, s0, -16
	v_or_b32_e32 v175, s24, v167
	s_add_i32 s16, s16, 16
	s_mov_b32 s17, 0
	v_mov_b64_e32 v[42:43], 0
	v_mov_b64_e32 v[44:45], 0
	v_mov_b64_e32 v[46:47], 0
	v_mov_b64_e32 v[48:49], 0
	v_mov_b64_e32 v[50:51], 0
	v_mov_b64_e32 v[52:53], 0
	v_mov_b64_e32 v[54:55], 0
	v_mov_b64_e32 v[56:57], 0
	v_mov_b64_e32 v[58:59], 0
	v_mov_b64_e32 v[60:61], 0
	v_mov_b64_e32 v[62:63], 0
	v_mov_b64_e32 v[64:65], 0
	v_mov_b64_e32 v[66:67], 0
	v_mov_b64_e32 v[68:69], 0
	v_mov_b64_e32 v[70:71], 0
	v_mov_b64_e32 v[72:73], 0
	v_mov_b64_e32 v[74:75], 0
	v_mov_b64_e32 v[76:77], 0
	v_mov_b64_e32 v[78:79], 0
	v_mov_b64_e32 v[80:81], 0
	v_mov_b64_e32 v[82:83], 0
	v_mov_b64_e32 v[84:85], 0
	v_mov_b64_e32 v[86:87], 0
	v_mov_b64_e32 v[88:89], 0
	v_mov_b64_e32 v[90:91], 0
	v_mov_b64_e32 v[92:93], 0
	v_mov_b64_e32 v[94:95], 0
	v_mov_b64_e32 v[96:97], 0
	v_mov_b64_e32 v[98:99], 0
	v_mov_b64_e32 v[100:101], 0
	v_mov_b64_e32 v[102:103], 0
	v_mov_b64_e32 v[104:105], 0
	v_mov_b64_e32 v[106:107], 0
	v_mov_b64_e32 v[108:109], 0
	v_mov_b64_e32 v[110:111], 0
	v_mov_b64_e32 v[112:113], 0
	v_mov_b64_e32 v[114:115], 0
	v_mov_b32_e32 v117, 0
	v_mov_b64_e32 v[118:119], 0
	v_mov_b64_e32 v[120:121], 0
	v_mov_b64_e32 v[122:123], 0
	v_mov_b64_e32 v[124:125], 0
	v_mov_b64_e32 v[126:127], 0
	v_mov_b64_e32 v[128:129], 0
	v_mov_b64_e32 v[130:131], 0
	v_mov_b64_e32 v[132:133], 0
	v_mov_b64_e32 v[134:135], 0
	v_mov_b64_e32 v[136:137], 0
	v_mov_b64_e32 v[138:139], 0
	v_mov_b64_e32 v[140:141], 0
	v_mov_b64_e32 v[142:143], 0
	v_mov_b64_e32 v[144:145], 0
	v_mov_b64_e32 v[146:147], 0
	v_mov_b64_e32 v[148:149], 0
	v_mov_b64_e32 v[150:151], 0
	v_mov_b64_e32 v[152:153], 0
	v_mov_b64_e32 v[154:155], 0
	v_mov_b64_e32 v[156:157], 0
	v_mov_b64_e32 v[158:159], 0
	v_mov_b64_e32 v[160:161], 0
	v_mov_b64_e32 v[162:163], 0
	v_mov_b64_e32 v[164:165], 0
	v_mov_b32_e32 v166, 0
	v_mov_b64_e32 v[168:169], 0
	v_mov_b64_e32 v[170:171], 0
	v_mov_b32_e32 v176, v41
	s_mov_b32 s18, 0
	s_mov_b32 s19, 0
	s_branch .LBB0_1296

.LBB0_1383:
	v_mov_b64_e32 v[42:43], 0
	v_mov_b64_e32 v[44:45], 0
	v_mov_b64_e32 v[46:47], 0
	v_mov_b64_e32 v[48:49], 0
	v_mov_b64_e32 v[50:51], 0
	v_mov_b64_e32 v[52:53], 0
	v_mov_b64_e32 v[54:55], 0
	v_mov_b64_e32 v[56:57], 0
	v_mov_b64_e32 v[58:59], 0
	v_mov_b64_e32 v[60:61], 0
	v_mov_b64_e32 v[62:63], 0
	v_mov_b64_e32 v[64:65], 0
	v_mov_b64_e32 v[66:67], 0
	v_mov_b64_e32 v[68:69], 0
	v_mov_b64_e32 v[70:71], 0
	v_mov_b64_e32 v[72:73], 0
	v_mov_b64_e32 v[74:75], 0
	v_mov_b64_e32 v[76:77], 0
	v_mov_b64_e32 v[78:79], 0
	v_mov_b64_e32 v[80:81], 0
	v_mov_b64_e32 v[82:83], 0
	v_mov_b64_e32 v[84:85], 0
	v_mov_b64_e32 v[86:87], 0
	v_mov_b64_e32 v[88:89], 0
	v_mov_b64_e32 v[90:91], 0
	v_mov_b64_e32 v[92:93], 0
	v_mov_b64_e32 v[94:95], 0
	v_mov_b64_e32 v[96:97], 0
	v_mov_b64_e32 v[98:99], 0
	v_mov_b64_e32 v[100:101], 0
	v_mov_b64_e32 v[102:103], 0
	v_mov_b64_e32 v[104:105], 0
	v_mov_b64_e32 v[106:107], 0
	v_mov_b64_e32 v[108:109], 0
	v_mov_b64_e32 v[110:111], 0
	v_mov_b64_e32 v[112:113], 0
	v_mov_b64_e32 v[114:115], 0
	v_mov_b32_e32 v117, 0
	v_mov_b64_e32 v[118:119], 0
	v_mov_b64_e32 v[120:121], 0
	v_mov_b64_e32 v[122:123], 0
	v_mov_b64_e32 v[124:125], 0
	v_mov_b64_e32 v[126:127], 0
	v_mov_b64_e32 v[128:129], 0
	v_mov_b64_e32 v[130:131], 0
	v_mov_b64_e32 v[132:133], 0
	v_mov_b64_e32 v[134:135], 0
	v_mov_b64_e32 v[136:137], 0
	v_mov_b64_e32 v[138:139], 0
	v_mov_b64_e32 v[140:141], 0
	v_mov_b64_e32 v[142:143], 0
	v_mov_b64_e32 v[144:145], 0
	v_mov_b64_e32 v[146:147], 0
	v_mov_b64_e32 v[148:149], 0
	v_mov_b64_e32 v[150:151], 0
	v_mov_b64_e32 v[152:153], 0
	v_mov_b64_e32 v[154:155], 0
	v_mov_b64_e32 v[156:157], 0
	v_mov_b64_e32 v[158:159], 0
	v_mov_b64_e32 v[160:161], 0
	v_mov_b64_e32 v[162:163], 0
	v_mov_b64_e32 v[164:165], 0
	v_mov_b32_e32 v166, 0
	v_mov_b64_e32 v[168:169], 0
	v_mov_b64_e32 v[170:171], 0
